# XH1: attention X head without VALU after the barrier release: LDS read addresses for the next X computed in the last P.V MFMA gaps of the previous X; on top of BE1
# baseline (speedup 1.0000x reference)
.LBB0_628:
	v_and_b32_e32 v5, 0x3fffffc0, v4
	s_add_i32 s8, 0, 0x18000
	v_lshl_add_u32 v171, v5, 2, s8
	s_add_i32 s8, 0, 0xc000
	s_cmp_lg_u32 s8, -1
	v_and_b32_e32 v169, 63, v4
	v_lshlrev_b32_e32 v4, 4, v4
	s_cselect_b32 s8, s8, 0
	v_and_b32_e32 v4, 0x70, v4
	v_lshl_add_u32 v7, v165, 8, s8
	v_or_b32_e32 v8, 32, v168
	v_xad_u32 v175, v8, v4, v7
	v_or_b32_e32 v8, 64, v168
	v_lshlrev_b32_e32 v5, 4, v169
	v_xad_u32 v176, v8, v4, v7
	v_or_b32_e32 v8, 0x60, v168
	s_mov_b32 s48, 2
	s_mov_b32 s49, 1
	v_lshlrev_b32_e32 v6, 1, v169
	s_mov_b32 s52, 0
	v_xad_u32 v174, v168, v4, v7
	v_xad_u32 v177, v8, v4, v7
	v_lshlrev_b32_e32 v66, 3, v169
	s_movk_i32 s50, 0xc0
	v_and_b32_e32 v67, 0xc0, v5
	v_and_b32_e32 v148, 32, v6
	ds_read_b128 v[4:7], v174 offset:0
	ds_read_b128 v[8:11], v174 offset:0x2000
	ds_read_b128 v[12:15], v175 offset:0
	ds_read_b128 v[42:45], v175 offset:0x2000
	ds_read_b128 v[46:49], v176 offset:0
	ds_read_b128 v[50:53], v176 offset:0x2000
	ds_read_b128 v[54:57], v177 offset:0
	ds_read_b128 v[58:61], v177 offset:0x2000
	s_waitcnt lgkmcnt(4)
	s_nop 0
	v_mfma_f32_32x32x16_bf16 v[84:99], v[4:7], v[128:131], 0
	s_mov_b32 s53, s52
	s_mov_b32 s54, s52
	s_mov_b32 s55, s52
	s_mov_b32 s56, s52
	s_mov_b32 s57, s52
	s_mov_b32 s58, s52
	s_mov_b32 s59, s52
	v_mfma_f32_32x32x16_bf16 v[68:83], v[8:11], v[128:131], 0
	s_mov_b32 s60, s52
	s_mov_b32 s61, s52
	s_mov_b32 s62, s52
	s_mov_b32 s63, s52
	s_mov_b32 s64, s52
	s_mov_b32 s65, s52
	s_mov_b32 s66, s52
	v_mfma_f32_32x32x16_bf16 v[84:99], v[12:15], v[124:127], v[84:99]
	s_mov_b32 s67, s52
	v_mov_b64_e32 v[4:5], s[52:53]
	v_mov_b64_e32 v[6:7], s[54:55]
	v_mov_b64_e32 v[8:9], s[56:57]
	v_mov_b64_e32 v[10:11], s[58:59]
	v_mov_b64_e32 v[12:13], s[60:61]
	v_mov_b64_e32 v[14:15], s[62:63]
	v_mfma_f32_32x32x16_bf16 v[68:83], v[42:45], v[124:127], v[68:83]
	v_mov_b64_e32 v[16:17], s[64:65]
	v_mov_b64_e32 v[18:19], s[66:67]
	ds_read_b128 v[42:45], v174 offset:0x80
	ds_read_b128 v[62:65], v174 offset:0x2080
	ds_read_b128 v[132:135], v175 offset:0x80
	ds_read_b128 v[136:139], v175 offset:0x2080
	s_waitcnt lgkmcnt(4)
	v_mfma_f32_32x32x16_bf16 v[84:99], v[46:49], v[120:123], v[84:99]
	v_mfma_f32_32x32x16_bf16 v[68:83], v[50:53], v[120:123], v[68:83]
	v_mfma_f32_32x32x16_bf16 v[84:99], v[54:57], v[116:119], v[84:99]
	v_mfma_f32_32x32x16_bf16 v[68:83], v[58:61], v[116:119], v[68:83]
	ds_read_b128 v[46:49], v176 offset:0x80
	ds_read_b128 v[50:53], v176 offset:0x2080
	ds_read_b128 v[54:57], v177 offset:0x80
	ds_read_b128 v[58:61], v177 offset:0x2080
	s_waitcnt lgkmcnt(4)
	v_mfma_f32_32x32x16_bf16 v[84:99], v[42:45], v[112:115], v[84:99]
	v_mfma_f32_32x32x16_bf16 v[68:83], v[62:65], v[112:115], v[68:83]
	v_mfma_f32_32x32x16_bf16 v[84:99], v[132:135], v[108:111], v[84:99]
	v_mfma_f32_32x32x16_bf16 v[68:83], v[136:139], v[108:111], v[68:83]
	s_waitcnt lgkmcnt(0)
	v_mfma_f32_32x32x16_bf16 v[84:99], v[46:49], v[104:107], v[84:99]
	v_mfma_f32_32x32x16_bf16 v[68:83], v[50:53], v[104:107], v[68:83]
	v_mfma_f32_32x32x16_bf16 v[84:99], v[54:57], v[100:103], v[84:99]
	v_mfma_f32_32x32x16_bf16 v[68:83], v[58:61], v[100:103], v[68:83]
	s_add_i32 s8, 0, 0x10000
	s_waitcnt vmcnt(0)
	s_waitcnt vmcnt(3)
	ds_write_b128 v40, v[20:23] offset:16384
	s_waitcnt vmcnt(2)
	ds_write_b128 v41, v[24:27] offset:16384
	v_add_u32_e32 v20, s8, v180
	s_waitcnt vmcnt(1)
	ds_write_b128 v20, v[28:31]
	v_add_u32_e32 v20, s8, v181
	s_waitcnt vmcnt(0)
	ds_write_b128 v20, v[32:35]
	v_add_co_u32_e32 v20, vcc, s22, v38
	s_nop 1
	v_addc_co_u32_e32 v21, vcc, 0, v39, vcc
	global_load_dwordx4 v[132:135], v[20:21], off
	v_add_co_u32_e32 v20, vcc, s24, v38
	s_nop 1
	v_addc_co_u32_e32 v21, vcc, 0, v39, vcc
	global_load_dwordx4 v[140:143], v[20:21], off
	v_add_co_u32_e32 v20, vcc, s22, v36
	s_nop 1
	v_addc_co_u32_e32 v21, vcc, 0, v37, vcc
	global_load_dwordx4 v[136:139], v[20:21], off
	v_add_co_u32_e32 v20, vcc, s24, v36
	s_nop 1
	v_addc_co_u32_e32 v21, vcc, 0, v37, vcc
	global_load_dwordx4 v[144:147], v[20:21], off
	s_waitcnt lgkmcnt(0)
	s_barrier
	s_movk_i32 s8, 0x118
	s_cmp_lg_u32 0, -1
	v_and_or_b32 v20, v66, s8, v148
	s_cselect_b32 s8, 0, 0
	v_add3_u32 v173, v67, s8, v20
	v_mov_b64_e32 v[66:67], v[18:19]
	v_mov_b64_e32 v[50:51], v[18:19]
	v_mov_b64_e32 v[34:35], v[18:19]
	v_cmp_gt_u32_e64 s[38:39], 32, v169
	v_lshl_add_u32 v172, v165, 2, v171
	v_mov_b32_e32 v183, 0
	v_mov_b32_e32 v182, 0xf149f2ca
	v_mov_b64_e32 v[64:65], v[16:17]
	v_mov_b64_e32 v[62:63], v[14:15]
	v_mov_b64_e32 v[60:61], v[12:13]
	v_mov_b64_e32 v[58:59], v[10:11]
	v_mov_b64_e32 v[56:57], v[8:9]
	v_mov_b64_e32 v[54:55], v[6:7]
	v_mov_b64_e32 v[52:53], v[4:5]
	v_mov_b64_e32 v[48:49], v[16:17]
	v_mov_b64_e32 v[46:47], v[14:15]
	v_mov_b64_e32 v[44:45], v[12:13]
	v_mov_b64_e32 v[42:43], v[10:11]
	v_mov_b64_e32 v[40:41], v[8:9]
	v_mov_b64_e32 v[38:39], v[6:7]
	v_mov_b64_e32 v[36:37], v[4:5]
	v_mov_b64_e32 v[32:33], v[16:17]
	v_mov_b64_e32 v[30:31], v[14:15]
	v_mov_b64_e32 v[28:29], v[12:13]
	v_mov_b64_e32 v[26:27], v[10:11]
	v_mov_b64_e32 v[24:25], v[8:9]
	v_mov_b64_e32 v[22:23], v[6:7]
	v_mov_b64_e32 v[20:21], v[4:5]
	s_mov_b32 s51, 2
	v_lshl_add_u32 v187, s52, 14, v173
	s_lshl_b32 s19, s49, 14
	v_add_u32_e32 v208, s19, v174
	v_add_u32_e32 v209, s19, v175
	v_add_u32_e32 v210, s19, v176
	v_add_u32_e32 v211, s19, v177
	s_branch .LBB0_629

.LBB0_633:
	s_waitcnt lgkmcnt(0)
	s_barrier
	ds_read_b64_tr_b16 v[188:189], v187 offset:0
	ds_read_b64_tr_b16 v[190:191], v187 offset:0x800
	ds_read_b64_tr_b16 v[192:193], v187 offset:0x1000
	ds_read_b64_tr_b16 v[194:195], v187 offset:0x1800
	ds_read_b64_tr_b16 v[196:197], v187 offset:0x2000
	ds_read_b64_tr_b16 v[198:199], v187 offset:0x2800
	ds_read_b64_tr_b16 v[200:201], v187 offset:0x3000
	ds_read_b64_tr_b16 v[202:203], v187 offset:0x3800
	s_lshl_b32 s52, s49, 14
	ds_read_b128 v[68:71], v208 offset:0
	ds_read_b128 v[72:75], v208 offset:0x2000
	ds_read_b128 v[204:207], v209 offset:0
	ds_read_b128 v[216:219], v209 offset:0x2000
	ds_read_b128 v[220:223], v210 offset:0
	ds_read_b128 v[224:227], v210 offset:0x2000
	ds_read_b128 v[228:231], v211 offset:0
	ds_read_b128 v[232:235], v211 offset:0x2000
	s_waitcnt lgkmcnt(4)
	v_mfma_f32_32x32x16_bf16 v[84:99], v[68:71], v[128:131], 0
	v_mfma_f32_32x32x16_bf16 v[68:83], v[72:75], v[128:131], 0
	v_mfma_f32_32x32x16_bf16 v[84:99], v[204:207], v[124:127], v[84:99]
	v_mfma_f32_32x32x16_bf16 v[68:83], v[216:219], v[124:127], v[68:83]
	ds_read_b128 v[204:207], v208 offset:0x80
	ds_read_b128 v[216:219], v208 offset:0x2080
	ds_read_b128 v[236:239], v209 offset:0x80
	ds_read_b128 v[242:245], v209 offset:0x2080
	s_waitcnt lgkmcnt(4)
	v_mfma_f32_32x32x16_bf16 v[84:99], v[220:223], v[120:123], v[84:99]
	v_mfma_f32_32x32x16_bf16 v[68:83], v[224:227], v[120:123], v[68:83]
	v_mfma_f32_32x32x16_bf16 v[84:99], v[228:231], v[116:119], v[84:99]
	v_mfma_f32_32x32x16_bf16 v[68:83], v[232:235], v[116:119], v[68:83]
	ds_read_b128 v[220:223], v210 offset:0x80
	ds_read_b128 v[224:227], v210 offset:0x2080
	ds_read_b128 v[228:231], v211 offset:0x80
	ds_read_b128 v[232:235], v211 offset:0x2080
	s_waitcnt lgkmcnt(4)
	v_mfma_f32_32x32x16_bf16 v[84:99], v[204:207], v[112:115], v[84:99]
	v_mfma_f32_32x32x16_bf16 v[68:83], v[216:219], v[112:115], v[68:83]
	v_mfma_f32_32x32x16_bf16 v[84:99], v[236:239], v[108:111], v[84:99]
	v_mfma_f32_32x32x16_bf16 v[68:83], v[242:245], v[108:111], v[68:83]
	s_waitcnt lgkmcnt(0)
	v_mfma_f32_32x32x16_bf16 v[84:99], v[220:223], v[104:107], v[84:99]
	v_mfma_f32_32x32x16_bf16 v[68:83], v[224:227], v[104:107], v[68:83]
	v_mfma_f32_32x32x16_bf16 v[84:99], v[228:231], v[100:103], v[84:99]
	v_mfma_f32_32x32x16_bf16 v[68:83], v[232:235], v[100:103], v[68:83]
	ds_read_b64_tr_b16 v[204:205], v187 offset:0x200
	ds_read_b64_tr_b16 v[206:207], v187 offset:0xa00
	ds_read_b64_tr_b16 v[216:217], v187 offset:0x1200
	ds_read_b64_tr_b16 v[218:219], v187 offset:0x1a00
	ds_read_b64_tr_b16 v[220:221], v187 offset:0x2200
	ds_read_b64_tr_b16 v[222:223], v187 offset:0x2a00
	ds_read_b64_tr_b16 v[224:225], v187 offset:0x3200
	ds_read_b64_tr_b16 v[226:227], v187 offset:0x3a00
	s_waitcnt lgkmcnt(8)
	v_mfma_f32_32x32x16_bf16 v[4:19], v[148:151], v[188:191], v[4:19]
	s_lshl_b32 s19, s51, 14
	s_add_i32 s8, s19, 0
	v_add_u32_e32 v236, s8, v179
	s_waitcnt vmcnt(0)
	v_mfma_f32_32x32x16_bf16 v[4:19], v[152:155], v[192:195], v[4:19]
	ds_write_b128 v236, v[144:147]
	v_add_u32_e32 v236, s8, v178
	v_mfma_f32_32x32x16_bf16 v[4:19], v[156:159], v[196:199], v[4:19]
	ds_write_b128 v236, v[136:139]
	v_add_u32_e32 v236, s8, v180
	v_mfma_f32_32x32x16_bf16 v[4:19], v[160:163], v[200:203], v[4:19]
	ds_read_b64_tr_b16 v[188:189], v187 offset:0x400
	ds_read_b64_tr_b16 v[190:191], v187 offset:0xc00
	ds_read_b64_tr_b16 v[192:193], v187 offset:0x1400
	ds_read_b64_tr_b16 v[194:195], v187 offset:0x1c00
	ds_read_b64_tr_b16 v[196:197], v187 offset:0x2400
	ds_read_b64_tr_b16 v[198:199], v187 offset:0x2c00
	ds_read_b64_tr_b16 v[200:201], v187 offset:0x3400
	ds_read_b64_tr_b16 v[202:203], v187 offset:0x3c00
	s_waitcnt lgkmcnt(10)
	v_mfma_f32_32x32x16_bf16 v[52:67], v[148:151], v[204:207], v[52:67]
	ds_write_b128 v236, v[140:143] offset:49152
	v_add_u32_e32 v236, s8, v181
	v_mfma_f32_32x32x16_bf16 v[52:67], v[152:155], v[216:219], v[52:67]
	ds_write_b128 v236, v[132:135] offset:49152
	s_add_i32 s48, s48, 1
	v_mfma_f32_32x32x16_bf16 v[52:67], v[156:159], v[220:223], v[52:67]
	s_sub_i32 s8, s50, s47
	s_min_u32 s36, s50, s8
	s_lshl_b64 s[8:9], s[36:37], 10
	s_cmp_lt_u32 s50, s47
	s_cselect_b32 s16, s30, s20
	s_cselect_b32 s17, s31, s21
	v_mfma_f32_32x32x16_bf16 v[52:67], v[160:163], v[224:227], v[52:67]
	ds_read_b64_tr_b16 v[204:205], v187 offset:0x600
	ds_read_b64_tr_b16 v[206:207], v187 offset:0xe00
	ds_read_b64_tr_b16 v[216:217], v187 offset:0x1600
	ds_read_b64_tr_b16 v[218:219], v187 offset:0x1e00
	ds_read_b64_tr_b16 v[220:221], v187 offset:0x2600
	ds_read_b64_tr_b16 v[222:223], v187 offset:0x2e00
	ds_read_b64_tr_b16 v[224:225], v187 offset:0x3600
	ds_read_b64_tr_b16 v[226:227], v187 offset:0x3e00
	s_waitcnt lgkmcnt(10)
	v_mfma_f32_32x32x16_bf16 v[36:51], v[148:151], v[188:191], v[36:51]
	s_cselect_b32 s36, s42, s26
	s_cselect_b32 s54, s43, s27
	s_add_u32 s16, s16, s8
	s_addc_u32 s17, s17, s9
	s_add_u32 s8, s36, s8
	s_addc_u32 s9, s54, s9
	v_mfma_f32_32x32x16_bf16 v[36:51], v[152:155], v[192:195], v[36:51]
	global_load_dwordx4 v[144:147], v2, s[8:9]
	s_add_u32 s8, s8, 0x8000
	s_addc_u32 s9, s9, 0
	v_mfma_f32_32x32x16_bf16 v[36:51], v[156:159], v[196:199], v[36:51]
	global_load_dwordx4 v[136:139], v2, s[8:9]
	global_load_dwordx4 v[140:143], v2, s[16:17]
	v_mfma_f32_32x32x16_bf16 v[36:51], v[160:163], v[200:203], v[36:51]
	s_add_u32 s16, s16, 0x8000
	s_addc_u32 s17, s17, 0
	global_load_dwordx4 v[132:135], v2, s[16:17]
	s_waitcnt lgkmcnt(0)
	v_mfma_f32_32x32x16_bf16 v[20:35], v[148:151], v[204:207], v[20:35]
	v_add_u32_e32 v187, s52, v173
	v_add_u32_e32 v208, s19, v174
	v_mfma_f32_32x32x16_bf16 v[20:35], v[152:155], v[216:219], v[20:35]
	v_add_u32_e32 v209, s19, v175
	v_add_u32_e32 v210, s19, v176
	v_mfma_f32_32x32x16_bf16 v[20:35], v[156:159], v[220:223], v[20:35]
	v_add_u32_e32 v211, s19, v177
	v_mfma_f32_32x32x16_bf16 v[20:35], v[160:163], v[224:227], v[20:35]
